# P3 gate epilogue hand-written: packed mul/add in the sigmoid, single v_med3 clamp (31% fewer VALU)
# speedup vs baseline: 1.0087x; 1.0087x over previous
.LBB0_606:
	s_add_i32 s99, s98, s87
	s_lshl_b32 s99, s99, 17
	s_add_u32 s100, s38, 0xba00000
	s_addc_u32 s101, s39, 0
	s_add_u32 s100, s100, s99
	s_addc_u32 s101, s101, 0
	v_lshrrev_b32_e32 v2, 6, v175
	v_mul_u32_u24_e32 v2, 0x3c00, v2
	v_lshl_add_u32 v2, v175, 4, v2
	v_mov_b32_e32 v3, 0
	v_lshl_add_u64 v[2:3], s[100:101], 0, v[2:3]
	s_mov_b32 s100, 0xbfb8aa3b
	s_mov_b32 s101, 0xbfb8aa3b
	v_med3_f32 v128, v128, s81, v176
	v_med3_f32 v129, v129, s81, v176
	v_med3_f32 v130, v130, s81, v176
	v_med3_f32 v131, v131, s81, v176
	v_med3_f32 v124, v124, s81, v176
	v_med3_f32 v125, v125, s81, v176
	v_med3_f32 v126, v126, s81, v176
	v_med3_f32 v127, v127, s81, v176
	v_pk_mul_f32 v[128:129], v[128:129], s[100:101] op_sel_hi:[1,0]
	v_pk_mul_f32 v[130:131], v[130:131], s[100:101] op_sel_hi:[1,0]
	v_pk_mul_f32 v[124:125], v[124:125], s[100:101] op_sel_hi:[1,0]
	v_pk_mul_f32 v[126:127], v[126:127], s[100:101] op_sel_hi:[1,0]
	v_exp_f32_e32 v128, v128
	v_exp_f32_e32 v129, v129
	v_exp_f32_e32 v130, v130
	v_exp_f32_e32 v131, v131
	v_exp_f32_e32 v124, v124
	v_exp_f32_e32 v125, v125
	v_exp_f32_e32 v126, v126
	v_exp_f32_e32 v127, v127
	v_pk_add_f32 v[128:129], v[128:129], 1.0 op_sel_hi:[1,0]
	v_pk_add_f32 v[130:131], v[130:131], 1.0 op_sel_hi:[1,0]
	v_pk_add_f32 v[124:125], v[124:125], 1.0 op_sel_hi:[1,0]
	v_pk_add_f32 v[126:127], v[126:127], 1.0 op_sel_hi:[1,0]
	v_rcp_f32_e32 v128, v128
	v_rcp_f32_e32 v129, v129
	v_rcp_f32_e32 v130, v130
	v_rcp_f32_e32 v131, v131
	v_rcp_f32_e32 v124, v124
	v_rcp_f32_e32 v125, v125
	v_rcp_f32_e32 v126, v126
	v_rcp_f32_e32 v127, v127
	v_cvt_pk_bf16_f32 v132, v128, v129
	v_cvt_pk_bf16_f32 v133, v130, v131
	v_cvt_pk_bf16_f32 v134, v124, v125
	v_cvt_pk_bf16_f32 v135, v126, v127
	flat_store_dwordx4 v[2:3], v[132:135]
	v_med3_f32 v120, v120, s81, v176
	v_med3_f32 v121, v121, s81, v176
	v_med3_f32 v122, v122, s81, v176
	v_med3_f32 v123, v123, s81, v176
	v_med3_f32 v116, v116, s81, v176
	v_med3_f32 v117, v117, s81, v176
	v_med3_f32 v118, v118, s81, v176
	v_med3_f32 v119, v119, s81, v176
	v_pk_mul_f32 v[120:121], v[120:121], s[100:101] op_sel_hi:[1,0]
	v_pk_mul_f32 v[122:123], v[122:123], s[100:101] op_sel_hi:[1,0]
	v_pk_mul_f32 v[116:117], v[116:117], s[100:101] op_sel_hi:[1,0]
	v_pk_mul_f32 v[118:119], v[118:119], s[100:101] op_sel_hi:[1,0]
	v_exp_f32_e32 v120, v120
	v_exp_f32_e32 v121, v121
	v_exp_f32_e32 v122, v122
	v_exp_f32_e32 v123, v123
	v_exp_f32_e32 v116, v116
	v_exp_f32_e32 v117, v117
	v_exp_f32_e32 v118, v118
	v_exp_f32_e32 v119, v119
	v_pk_add_f32 v[120:121], v[120:121], 1.0 op_sel_hi:[1,0]
	v_pk_add_f32 v[122:123], v[122:123], 1.0 op_sel_hi:[1,0]
	v_pk_add_f32 v[116:117], v[116:117], 1.0 op_sel_hi:[1,0]
	v_pk_add_f32 v[118:119], v[118:119], 1.0 op_sel_hi:[1,0]
	v_rcp_f32_e32 v120, v120
	v_rcp_f32_e32 v121, v121
	v_rcp_f32_e32 v122, v122
	v_rcp_f32_e32 v123, v123
	v_rcp_f32_e32 v116, v116
	v_rcp_f32_e32 v117, v117
	v_rcp_f32_e32 v118, v118
	v_rcp_f32_e32 v119, v119
	v_cvt_pk_bf16_f32 v140, v120, v121
	v_cvt_pk_bf16_f32 v141, v122, v123
	v_cvt_pk_bf16_f32 v142, v116, v117
	v_cvt_pk_bf16_f32 v143, v118, v119
	flat_store_dwordx4 v[2:3], v[140:143] offset:1024
	v_lshl_add_u64 v[2:3], v[2:3], 0, s[20:21]
	v_med3_f32 v112, v112, s81, v176
	v_med3_f32 v113, v113, s81, v176
	v_med3_f32 v114, v114, s81, v176
	v_med3_f32 v115, v115, s81, v176
	v_med3_f32 v108, v108, s81, v176
	v_med3_f32 v109, v109, s81, v176
	v_med3_f32 v110, v110, s81, v176
	v_med3_f32 v111, v111, s81, v176
	v_pk_mul_f32 v[112:113], v[112:113], s[100:101] op_sel_hi:[1,0]
	v_pk_mul_f32 v[114:115], v[114:115], s[100:101] op_sel_hi:[1,0]
	v_pk_mul_f32 v[108:109], v[108:109], s[100:101] op_sel_hi:[1,0]
	v_pk_mul_f32 v[110:111], v[110:111], s[100:101] op_sel_hi:[1,0]
	v_exp_f32_e32 v112, v112
	v_exp_f32_e32 v113, v113
	v_exp_f32_e32 v114, v114
	v_exp_f32_e32 v115, v115
	v_exp_f32_e32 v108, v108
	v_exp_f32_e32 v109, v109
	v_exp_f32_e32 v110, v110
	v_exp_f32_e32 v111, v111
	v_pk_add_f32 v[112:113], v[112:113], 1.0 op_sel_hi:[1,0]
	v_pk_add_f32 v[114:115], v[114:115], 1.0 op_sel_hi:[1,0]
	v_pk_add_f32 v[108:109], v[108:109], 1.0 op_sel_hi:[1,0]
	v_pk_add_f32 v[110:111], v[110:111], 1.0 op_sel_hi:[1,0]
	v_rcp_f32_e32 v112, v112
	v_rcp_f32_e32 v113, v113
	v_rcp_f32_e32 v114, v114
	v_rcp_f32_e32 v115, v115
	v_rcp_f32_e32 v108, v108
	v_rcp_f32_e32 v109, v109
	v_rcp_f32_e32 v110, v110
	v_rcp_f32_e32 v111, v111
	v_cvt_pk_bf16_f32 v132, v112, v113
	v_cvt_pk_bf16_f32 v133, v114, v115
	v_cvt_pk_bf16_f32 v134, v108, v109
	v_cvt_pk_bf16_f32 v135, v110, v111
	flat_store_dwordx4 v[2:3], v[132:135]
	v_med3_f32 v104, v104, s81, v176
	v_med3_f32 v105, v105, s81, v176
	v_med3_f32 v106, v106, s81, v176
	v_med3_f32 v107, v107, s81, v176
	v_med3_f32 v100, v100, s81, v176
	v_med3_f32 v101, v101, s81, v176
	v_med3_f32 v102, v102, s81, v176
	v_med3_f32 v103, v103, s81, v176
	v_pk_mul_f32 v[104:105], v[104:105], s[100:101] op_sel_hi:[1,0]
	v_pk_mul_f32 v[106:107], v[106:107], s[100:101] op_sel_hi:[1,0]
	v_pk_mul_f32 v[100:101], v[100:101], s[100:101] op_sel_hi:[1,0]
	v_pk_mul_f32 v[102:103], v[102:103], s[100:101] op_sel_hi:[1,0]
	v_exp_f32_e32 v104, v104
	v_exp_f32_e32 v105, v105
	v_exp_f32_e32 v106, v106
	v_exp_f32_e32 v107, v107
	v_exp_f32_e32 v100, v100
	v_exp_f32_e32 v101, v101
	v_exp_f32_e32 v102, v102
	v_exp_f32_e32 v103, v103
	v_pk_add_f32 v[104:105], v[104:105], 1.0 op_sel_hi:[1,0]
	v_pk_add_f32 v[106:107], v[106:107], 1.0 op_sel_hi:[1,0]
	v_pk_add_f32 v[100:101], v[100:101], 1.0 op_sel_hi:[1,0]
	v_pk_add_f32 v[102:103], v[102:103], 1.0 op_sel_hi:[1,0]
	v_rcp_f32_e32 v104, v104
	v_rcp_f32_e32 v105, v105
	v_rcp_f32_e32 v106, v106
	v_rcp_f32_e32 v107, v107
	v_rcp_f32_e32 v100, v100
	v_rcp_f32_e32 v101, v101
	v_rcp_f32_e32 v102, v102
	v_rcp_f32_e32 v103, v103
	v_cvt_pk_bf16_f32 v140, v104, v105
	v_cvt_pk_bf16_f32 v141, v106, v107
	v_cvt_pk_bf16_f32 v142, v100, v101
	v_cvt_pk_bf16_f32 v143, v102, v103
	flat_store_dwordx4 v[2:3], v[140:143] offset:1024
	v_lshl_add_u64 v[2:3], v[2:3], 0, s[20:21]
	v_med3_f32 v96, v96, s81, v176
	v_med3_f32 v97, v97, s81, v176
	v_med3_f32 v98, v98, s81, v176
	v_med3_f32 v99, v99, s81, v176
	v_med3_f32 v92, v92, s81, v176
	v_med3_f32 v93, v93, s81, v176
	v_med3_f32 v94, v94, s81, v176
	v_med3_f32 v95, v95, s81, v176
	v_pk_mul_f32 v[96:97], v[96:97], s[100:101] op_sel_hi:[1,0]
	v_pk_mul_f32 v[98:99], v[98:99], s[100:101] op_sel_hi:[1,0]
	v_pk_mul_f32 v[92:93], v[92:93], s[100:101] op_sel_hi:[1,0]
	v_pk_mul_f32 v[94:95], v[94:95], s[100:101] op_sel_hi:[1,0]
	v_exp_f32_e32 v96, v96
	v_exp_f32_e32 v97, v97
	v_exp_f32_e32 v98, v98
	v_exp_f32_e32 v99, v99
	v_exp_f32_e32 v92, v92
	v_exp_f32_e32 v93, v93
	v_exp_f32_e32 v94, v94
	v_exp_f32_e32 v95, v95
	v_pk_add_f32 v[96:97], v[96:97], 1.0 op_sel_hi:[1,0]
	v_pk_add_f32 v[98:99], v[98:99], 1.0 op_sel_hi:[1,0]
	v_pk_add_f32 v[92:93], v[92:93], 1.0 op_sel_hi:[1,0]
	v_pk_add_f32 v[94:95], v[94:95], 1.0 op_sel_hi:[1,0]
	v_rcp_f32_e32 v96, v96
	v_rcp_f32_e32 v97, v97
	v_rcp_f32_e32 v98, v98
	v_rcp_f32_e32 v99, v99
	v_rcp_f32_e32 v92, v92
	v_rcp_f32_e32 v93, v93
	v_rcp_f32_e32 v94, v94
	v_rcp_f32_e32 v95, v95
	v_cvt_pk_bf16_f32 v132, v96, v97
	v_cvt_pk_bf16_f32 v133, v98, v99
	v_cvt_pk_bf16_f32 v134, v92, v93
	v_cvt_pk_bf16_f32 v135, v94, v95
	flat_store_dwordx4 v[2:3], v[132:135]
	v_med3_f32 v88, v88, s81, v176
	v_med3_f32 v89, v89, s81, v176
	v_med3_f32 v90, v90, s81, v176
	v_med3_f32 v91, v91, s81, v176
	v_med3_f32 v84, v84, s81, v176
	v_med3_f32 v85, v85, s81, v176
	v_med3_f32 v86, v86, s81, v176
	v_med3_f32 v87, v87, s81, v176
	v_pk_mul_f32 v[88:89], v[88:89], s[100:101] op_sel_hi:[1,0]
	v_pk_mul_f32 v[90:91], v[90:91], s[100:101] op_sel_hi:[1,0]
	v_pk_mul_f32 v[84:85], v[84:85], s[100:101] op_sel_hi:[1,0]
	v_pk_mul_f32 v[86:87], v[86:87], s[100:101] op_sel_hi:[1,0]
	v_exp_f32_e32 v88, v88
	v_exp_f32_e32 v89, v89
	v_exp_f32_e32 v90, v90
	v_exp_f32_e32 v91, v91
	v_exp_f32_e32 v84, v84
	v_exp_f32_e32 v85, v85
	v_exp_f32_e32 v86, v86
	v_exp_f32_e32 v87, v87
	v_pk_add_f32 v[88:89], v[88:89], 1.0 op_sel_hi:[1,0]
	v_pk_add_f32 v[90:91], v[90:91], 1.0 op_sel_hi:[1,0]
	v_pk_add_f32 v[84:85], v[84:85], 1.0 op_sel_hi:[1,0]
	v_pk_add_f32 v[86:87], v[86:87], 1.0 op_sel_hi:[1,0]
	v_rcp_f32_e32 v88, v88
	v_rcp_f32_e32 v89, v89
	v_rcp_f32_e32 v90, v90
	v_rcp_f32_e32 v91, v91
	v_rcp_f32_e32 v84, v84
	v_rcp_f32_e32 v85, v85
	v_rcp_f32_e32 v86, v86
	v_rcp_f32_e32 v87, v87
	v_cvt_pk_bf16_f32 v140, v88, v89
	v_cvt_pk_bf16_f32 v141, v90, v91
	v_cvt_pk_bf16_f32 v142, v84, v85
	v_cvt_pk_bf16_f32 v143, v86, v87
	flat_store_dwordx4 v[2:3], v[140:143] offset:1024
	v_lshl_add_u64 v[2:3], v[2:3], 0, s[20:21]
	v_med3_f32 v80, v80, s81, v176
	v_med3_f32 v81, v81, s81, v176
	v_med3_f32 v82, v82, s81, v176
	v_med3_f32 v83, v83, s81, v176
	v_med3_f32 v76, v76, s81, v176
	v_med3_f32 v77, v77, s81, v176
	v_med3_f32 v78, v78, s81, v176
	v_med3_f32 v79, v79, s81, v176
	v_pk_mul_f32 v[80:81], v[80:81], s[100:101] op_sel_hi:[1,0]
	v_pk_mul_f32 v[82:83], v[82:83], s[100:101] op_sel_hi:[1,0]
	v_pk_mul_f32 v[76:77], v[76:77], s[100:101] op_sel_hi:[1,0]
	v_pk_mul_f32 v[78:79], v[78:79], s[100:101] op_sel_hi:[1,0]
	v_exp_f32_e32 v80, v80
	v_exp_f32_e32 v81, v81
	v_exp_f32_e32 v82, v82
	v_exp_f32_e32 v83, v83
	v_exp_f32_e32 v76, v76
	v_exp_f32_e32 v77, v77
	v_exp_f32_e32 v78, v78
	v_exp_f32_e32 v79, v79
	v_pk_add_f32 v[80:81], v[80:81], 1.0 op_sel_hi:[1,0]
	v_pk_add_f32 v[82:83], v[82:83], 1.0 op_sel_hi:[1,0]
	v_pk_add_f32 v[76:77], v[76:77], 1.0 op_sel_hi:[1,0]
	v_pk_add_f32 v[78:79], v[78:79], 1.0 op_sel_hi:[1,0]
	v_rcp_f32_e32 v80, v80
	v_rcp_f32_e32 v81, v81
	v_rcp_f32_e32 v82, v82
	v_rcp_f32_e32 v83, v83
	v_rcp_f32_e32 v76, v76
	v_rcp_f32_e32 v77, v77
	v_rcp_f32_e32 v78, v78
	v_rcp_f32_e32 v79, v79
	v_cvt_pk_bf16_f32 v132, v80, v81
	v_cvt_pk_bf16_f32 v133, v82, v83
	v_cvt_pk_bf16_f32 v134, v76, v77
	v_cvt_pk_bf16_f32 v135, v78, v79
	flat_store_dwordx4 v[2:3], v[132:135]
	v_med3_f32 v72, v72, s81, v176
	v_med3_f32 v73, v73, s81, v176
	v_med3_f32 v74, v74, s81, v176
	v_med3_f32 v75, v75, s81, v176
	v_med3_f32 v68, v68, s81, v176
	v_med3_f32 v69, v69, s81, v176
	v_med3_f32 v70, v70, s81, v176
	v_med3_f32 v71, v71, s81, v176
	v_pk_mul_f32 v[72:73], v[72:73], s[100:101] op_sel_hi:[1,0]
	v_pk_mul_f32 v[74:75], v[74:75], s[100:101] op_sel_hi:[1,0]
	v_pk_mul_f32 v[68:69], v[68:69], s[100:101] op_sel_hi:[1,0]
	v_pk_mul_f32 v[70:71], v[70:71], s[100:101] op_sel_hi:[1,0]
	v_exp_f32_e32 v72, v72
	v_exp_f32_e32 v73, v73
	v_exp_f32_e32 v74, v74
	v_exp_f32_e32 v75, v75
	v_exp_f32_e32 v68, v68
	v_exp_f32_e32 v69, v69
	v_exp_f32_e32 v70, v70
	v_exp_f32_e32 v71, v71
	v_pk_add_f32 v[72:73], v[72:73], 1.0 op_sel_hi:[1,0]
	v_pk_add_f32 v[74:75], v[74:75], 1.0 op_sel_hi:[1,0]
	v_pk_add_f32 v[68:69], v[68:69], 1.0 op_sel_hi:[1,0]
	v_pk_add_f32 v[70:71], v[70:71], 1.0 op_sel_hi:[1,0]
	v_rcp_f32_e32 v72, v72
	v_rcp_f32_e32 v73, v73
	v_rcp_f32_e32 v74, v74
	v_rcp_f32_e32 v75, v75
	v_rcp_f32_e32 v68, v68
	v_rcp_f32_e32 v69, v69
	v_rcp_f32_e32 v70, v70
	v_rcp_f32_e32 v71, v71
	v_cvt_pk_bf16_f32 v140, v72, v73
	v_cvt_pk_bf16_f32 v141, v74, v75
	v_cvt_pk_bf16_f32 v142, v68, v69
	v_cvt_pk_bf16_f32 v143, v70, v71
	flat_store_dwordx4 v[2:3], v[140:143] offset:1024
	v_lshl_add_u64 v[2:3], v[2:3], 0, s[20:21]
	v_med3_f32 v64, v64, s81, v176
	v_med3_f32 v65, v65, s81, v176
	v_med3_f32 v66, v66, s81, v176
	v_med3_f32 v67, v67, s81, v176
	v_med3_f32 v60, v60, s81, v176
	v_med3_f32 v61, v61, s81, v176
	v_med3_f32 v62, v62, s81, v176
	v_med3_f32 v63, v63, s81, v176
	v_pk_mul_f32 v[64:65], v[64:65], s[100:101] op_sel_hi:[1,0]
	v_pk_mul_f32 v[66:67], v[66:67], s[100:101] op_sel_hi:[1,0]
	v_pk_mul_f32 v[60:61], v[60:61], s[100:101] op_sel_hi:[1,0]
	v_pk_mul_f32 v[62:63], v[62:63], s[100:101] op_sel_hi:[1,0]
	v_exp_f32_e32 v64, v64
	v_exp_f32_e32 v65, v65
	v_exp_f32_e32 v66, v66
	v_exp_f32_e32 v67, v67
	v_exp_f32_e32 v60, v60
	v_exp_f32_e32 v61, v61
	v_exp_f32_e32 v62, v62
	v_exp_f32_e32 v63, v63
	v_pk_add_f32 v[64:65], v[64:65], 1.0 op_sel_hi:[1,0]
	v_pk_add_f32 v[66:67], v[66:67], 1.0 op_sel_hi:[1,0]
	v_pk_add_f32 v[60:61], v[60:61], 1.0 op_sel_hi:[1,0]
	v_pk_add_f32 v[62:63], v[62:63], 1.0 op_sel_hi:[1,0]
	v_rcp_f32_e32 v64, v64
	v_rcp_f32_e32 v65, v65
	v_rcp_f32_e32 v66, v66
	v_rcp_f32_e32 v67, v67
	v_rcp_f32_e32 v60, v60
	v_rcp_f32_e32 v61, v61
	v_rcp_f32_e32 v62, v62
	v_rcp_f32_e32 v63, v63
	v_cvt_pk_bf16_f32 v132, v64, v65
	v_cvt_pk_bf16_f32 v133, v66, v67
	v_cvt_pk_bf16_f32 v134, v60, v61
	v_cvt_pk_bf16_f32 v135, v62, v63
	flat_store_dwordx4 v[2:3], v[132:135]
	v_med3_f32 v56, v56, s81, v176
	v_med3_f32 v57, v57, s81, v176
	v_med3_f32 v58, v58, s81, v176
	v_med3_f32 v59, v59, s81, v176
	v_med3_f32 v52, v52, s81, v176
	v_med3_f32 v53, v53, s81, v176
	v_med3_f32 v54, v54, s81, v176
	v_med3_f32 v55, v55, s81, v176
	v_pk_mul_f32 v[56:57], v[56:57], s[100:101] op_sel_hi:[1,0]
	v_pk_mul_f32 v[58:59], v[58:59], s[100:101] op_sel_hi:[1,0]
	v_pk_mul_f32 v[52:53], v[52:53], s[100:101] op_sel_hi:[1,0]
	v_pk_mul_f32 v[54:55], v[54:55], s[100:101] op_sel_hi:[1,0]
	v_exp_f32_e32 v56, v56
	v_exp_f32_e32 v57, v57
	v_exp_f32_e32 v58, v58
	v_exp_f32_e32 v59, v59
	v_exp_f32_e32 v52, v52
	v_exp_f32_e32 v53, v53
	v_exp_f32_e32 v54, v54
	v_exp_f32_e32 v55, v55
	v_pk_add_f32 v[56:57], v[56:57], 1.0 op_sel_hi:[1,0]
	v_pk_add_f32 v[58:59], v[58:59], 1.0 op_sel_hi:[1,0]
	v_pk_add_f32 v[52:53], v[52:53], 1.0 op_sel_hi:[1,0]
	v_pk_add_f32 v[54:55], v[54:55], 1.0 op_sel_hi:[1,0]
	v_rcp_f32_e32 v56, v56
	v_rcp_f32_e32 v57, v57
	v_rcp_f32_e32 v58, v58
	v_rcp_f32_e32 v59, v59
	v_rcp_f32_e32 v52, v52
	v_rcp_f32_e32 v53, v53
	v_rcp_f32_e32 v54, v54
	v_rcp_f32_e32 v55, v55
	v_cvt_pk_bf16_f32 v140, v56, v57
	v_cvt_pk_bf16_f32 v141, v58, v59
	v_cvt_pk_bf16_f32 v142, v52, v53
	v_cvt_pk_bf16_f32 v143, v54, v55
	flat_store_dwordx4 v[2:3], v[140:143] offset:1024
	v_lshl_add_u64 v[2:3], v[2:3], 0, s[20:21]
	v_med3_f32 v48, v48, s81, v176
	v_med3_f32 v49, v49, s81, v176
	v_med3_f32 v50, v50, s81, v176
	v_med3_f32 v51, v51, s81, v176
	v_med3_f32 v44, v44, s81, v176
	v_med3_f32 v45, v45, s81, v176
	v_med3_f32 v46, v46, s81, v176
	v_med3_f32 v47, v47, s81, v176
	v_pk_mul_f32 v[48:49], v[48:49], s[100:101] op_sel_hi:[1,0]
	v_pk_mul_f32 v[50:51], v[50:51], s[100:101] op_sel_hi:[1,0]
	v_pk_mul_f32 v[44:45], v[44:45], s[100:101] op_sel_hi:[1,0]
	v_pk_mul_f32 v[46:47], v[46:47], s[100:101] op_sel_hi:[1,0]
	v_exp_f32_e32 v48, v48
	v_exp_f32_e32 v49, v49
	v_exp_f32_e32 v50, v50
	v_exp_f32_e32 v51, v51
	v_exp_f32_e32 v44, v44
	v_exp_f32_e32 v45, v45
	v_exp_f32_e32 v46, v46
	v_exp_f32_e32 v47, v47
	v_pk_add_f32 v[48:49], v[48:49], 1.0 op_sel_hi:[1,0]
	v_pk_add_f32 v[50:51], v[50:51], 1.0 op_sel_hi:[1,0]
	v_pk_add_f32 v[44:45], v[44:45], 1.0 op_sel_hi:[1,0]
	v_pk_add_f32 v[46:47], v[46:47], 1.0 op_sel_hi:[1,0]
	v_rcp_f32_e32 v48, v48
	v_rcp_f32_e32 v49, v49
	v_rcp_f32_e32 v50, v50
	v_rcp_f32_e32 v51, v51
	v_rcp_f32_e32 v44, v44
	v_rcp_f32_e32 v45, v45
	v_rcp_f32_e32 v46, v46
	v_rcp_f32_e32 v47, v47
	v_cvt_pk_bf16_f32 v132, v48, v49
	v_cvt_pk_bf16_f32 v133, v50, v51
	v_cvt_pk_bf16_f32 v134, v44, v45
	v_cvt_pk_bf16_f32 v135, v46, v47
	flat_store_dwordx4 v[2:3], v[132:135]
	v_med3_f32 v40, v40, s81, v176
	v_med3_f32 v41, v41, s81, v176
	v_med3_f32 v42, v42, s81, v176
	v_med3_f32 v43, v43, s81, v176
	v_med3_f32 v36, v36, s81, v176
	v_med3_f32 v37, v37, s81, v176
	v_med3_f32 v38, v38, s81, v176
	v_med3_f32 v39, v39, s81, v176
	v_pk_mul_f32 v[40:41], v[40:41], s[100:101] op_sel_hi:[1,0]
	v_pk_mul_f32 v[42:43], v[42:43], s[100:101] op_sel_hi:[1,0]
	v_pk_mul_f32 v[36:37], v[36:37], s[100:101] op_sel_hi:[1,0]
	v_pk_mul_f32 v[38:39], v[38:39], s[100:101] op_sel_hi:[1,0]
	v_exp_f32_e32 v40, v40
	v_exp_f32_e32 v41, v41
	v_exp_f32_e32 v42, v42
	v_exp_f32_e32 v43, v43
	v_exp_f32_e32 v36, v36
	v_exp_f32_e32 v37, v37
	v_exp_f32_e32 v38, v38
	v_exp_f32_e32 v39, v39
	v_pk_add_f32 v[40:41], v[40:41], 1.0 op_sel_hi:[1,0]
	v_pk_add_f32 v[42:43], v[42:43], 1.0 op_sel_hi:[1,0]
	v_pk_add_f32 v[36:37], v[36:37], 1.0 op_sel_hi:[1,0]
	v_pk_add_f32 v[38:39], v[38:39], 1.0 op_sel_hi:[1,0]
	v_rcp_f32_e32 v40, v40
	v_rcp_f32_e32 v41, v41
	v_rcp_f32_e32 v42, v42
	v_rcp_f32_e32 v43, v43
	v_rcp_f32_e32 v36, v36
	v_rcp_f32_e32 v37, v37
	v_rcp_f32_e32 v38, v38
	v_rcp_f32_e32 v39, v39
	v_cvt_pk_bf16_f32 v140, v40, v41
	v_cvt_pk_bf16_f32 v141, v42, v43
	v_cvt_pk_bf16_f32 v142, v36, v37
	v_cvt_pk_bf16_f32 v143, v38, v39
	flat_store_dwordx4 v[2:3], v[140:143] offset:1024
	v_lshl_add_u64 v[2:3], v[2:3], 0, s[20:21]
	v_med3_f32 v32, v32, s81, v176
	v_med3_f32 v33, v33, s81, v176
	v_med3_f32 v34, v34, s81, v176
	v_med3_f32 v35, v35, s81, v176
	v_med3_f32 v28, v28, s81, v176
	v_med3_f32 v29, v29, s81, v176
	v_med3_f32 v30, v30, s81, v176
	v_med3_f32 v31, v31, s81, v176
	v_pk_mul_f32 v[32:33], v[32:33], s[100:101] op_sel_hi:[1,0]
	v_pk_mul_f32 v[34:35], v[34:35], s[100:101] op_sel_hi:[1,0]
	v_pk_mul_f32 v[28:29], v[28:29], s[100:101] op_sel_hi:[1,0]
	v_pk_mul_f32 v[30:31], v[30:31], s[100:101] op_sel_hi:[1,0]
	v_exp_f32_e32 v32, v32
	v_exp_f32_e32 v33, v33
	v_exp_f32_e32 v34, v34
	v_exp_f32_e32 v35, v35
	v_exp_f32_e32 v28, v28
	v_exp_f32_e32 v29, v29
	v_exp_f32_e32 v30, v30
	v_exp_f32_e32 v31, v31
	v_pk_add_f32 v[32:33], v[32:33], 1.0 op_sel_hi:[1,0]
	v_pk_add_f32 v[34:35], v[34:35], 1.0 op_sel_hi:[1,0]
	v_pk_add_f32 v[28:29], v[28:29], 1.0 op_sel_hi:[1,0]
	v_pk_add_f32 v[30:31], v[30:31], 1.0 op_sel_hi:[1,0]
	v_rcp_f32_e32 v32, v32
	v_rcp_f32_e32 v33, v33
	v_rcp_f32_e32 v34, v34
	v_rcp_f32_e32 v35, v35
	v_rcp_f32_e32 v28, v28
	v_rcp_f32_e32 v29, v29
	v_rcp_f32_e32 v30, v30
	v_rcp_f32_e32 v31, v31
	v_cvt_pk_bf16_f32 v132, v32, v33
	v_cvt_pk_bf16_f32 v133, v34, v35
	v_cvt_pk_bf16_f32 v134, v28, v29
	v_cvt_pk_bf16_f32 v135, v30, v31
	flat_store_dwordx4 v[2:3], v[132:135]
	v_med3_f32 v24, v24, s81, v176
	v_med3_f32 v25, v25, s81, v176
	v_med3_f32 v26, v26, s81, v176
	v_med3_f32 v27, v27, s81, v176
	v_med3_f32 v20, v20, s81, v176
	v_med3_f32 v21, v21, s81, v176
	v_med3_f32 v22, v22, s81, v176
	v_med3_f32 v23, v23, s81, v176
	v_pk_mul_f32 v[24:25], v[24:25], s[100:101] op_sel_hi:[1,0]
	v_pk_mul_f32 v[26:27], v[26:27], s[100:101] op_sel_hi:[1,0]
	v_pk_mul_f32 v[20:21], v[20:21], s[100:101] op_sel_hi:[1,0]
	v_pk_mul_f32 v[22:23], v[22:23], s[100:101] op_sel_hi:[1,0]
	v_exp_f32_e32 v24, v24
	v_exp_f32_e32 v25, v25
	v_exp_f32_e32 v26, v26
	v_exp_f32_e32 v27, v27
	v_exp_f32_e32 v20, v20
	v_exp_f32_e32 v21, v21
	v_exp_f32_e32 v22, v22
	v_exp_f32_e32 v23, v23
	v_pk_add_f32 v[24:25], v[24:25], 1.0 op_sel_hi:[1,0]
	v_pk_add_f32 v[26:27], v[26:27], 1.0 op_sel_hi:[1,0]
	v_pk_add_f32 v[20:21], v[20:21], 1.0 op_sel_hi:[1,0]
	v_pk_add_f32 v[22:23], v[22:23], 1.0 op_sel_hi:[1,0]
	v_rcp_f32_e32 v24, v24
	v_rcp_f32_e32 v25, v25
	v_rcp_f32_e32 v26, v26
	v_rcp_f32_e32 v27, v27
	v_rcp_f32_e32 v20, v20
	v_rcp_f32_e32 v21, v21
	v_rcp_f32_e32 v22, v22
	v_rcp_f32_e32 v23, v23
	v_cvt_pk_bf16_f32 v140, v24, v25
	v_cvt_pk_bf16_f32 v141, v26, v27
	v_cvt_pk_bf16_f32 v142, v20, v21
	v_cvt_pk_bf16_f32 v143, v22, v23
	flat_store_dwordx4 v[2:3], v[140:143] offset:1024
	v_lshl_add_u64 v[2:3], v[2:3], 0, s[20:21]
	v_med3_f32 v16, v16, s81, v176
	v_med3_f32 v17, v17, s81, v176
	v_med3_f32 v18, v18, s81, v176
	v_med3_f32 v19, v19, s81, v176
	v_med3_f32 v12, v12, s81, v176
	v_med3_f32 v13, v13, s81, v176
	v_med3_f32 v14, v14, s81, v176
	v_med3_f32 v15, v15, s81, v176
	v_pk_mul_f32 v[16:17], v[16:17], s[100:101] op_sel_hi:[1,0]
	v_pk_mul_f32 v[18:19], v[18:19], s[100:101] op_sel_hi:[1,0]
	v_pk_mul_f32 v[12:13], v[12:13], s[100:101] op_sel_hi:[1,0]
	v_pk_mul_f32 v[14:15], v[14:15], s[100:101] op_sel_hi:[1,0]
	v_exp_f32_e32 v16, v16
	v_exp_f32_e32 v17, v17
	v_exp_f32_e32 v18, v18
	v_exp_f32_e32 v19, v19
	v_exp_f32_e32 v12, v12
	v_exp_f32_e32 v13, v13
	v_exp_f32_e32 v14, v14
	v_exp_f32_e32 v15, v15
	v_pk_add_f32 v[16:17], v[16:17], 1.0 op_sel_hi:[1,0]
	v_pk_add_f32 v[18:19], v[18:19], 1.0 op_sel_hi:[1,0]
	v_pk_add_f32 v[12:13], v[12:13], 1.0 op_sel_hi:[1,0]
	v_pk_add_f32 v[14:15], v[14:15], 1.0 op_sel_hi:[1,0]
	v_rcp_f32_e32 v16, v16
	v_rcp_f32_e32 v17, v17
	v_rcp_f32_e32 v18, v18
	v_rcp_f32_e32 v19, v19
	v_rcp_f32_e32 v12, v12
	v_rcp_f32_e32 v13, v13
	v_rcp_f32_e32 v14, v14
	v_rcp_f32_e32 v15, v15
	v_cvt_pk_bf16_f32 v132, v16, v17
	v_cvt_pk_bf16_f32 v133, v18, v19
	v_cvt_pk_bf16_f32 v134, v12, v13
	v_cvt_pk_bf16_f32 v135, v14, v15
	flat_store_dwordx4 v[2:3], v[132:135]
	v_med3_f32 v136, v6, s81, v176
	v_med3_f32 v137, v7, s81, v176
	v_mov_b32_e32 v138, 0
	v_mov_b32_e32 v139, 0
	v_med3_f32 v8, v8, s81, v176
	v_med3_f32 v9, v9, s81, v176
	v_med3_f32 v10, v10, s81, v176
	v_med3_f32 v11, v11, s81, v176
	v_med3_f32 v4, v4, s81, v176
	v_med3_f32 v5, v5, s81, v176
	v_pk_mul_f32 v[8:9], v[8:9], s[100:101] op_sel_hi:[1,0]
	v_pk_mul_f32 v[10:11], v[10:11], s[100:101] op_sel_hi:[1,0]
	v_pk_mul_f32 v[4:5], v[4:5], s[100:101] op_sel_hi:[1,0]
	v_pk_mul_f32 v[136:137], v[136:137], s[100:101] op_sel_hi:[1,0]
	v_exp_f32_e32 v8, v8
	v_exp_f32_e32 v9, v9
	v_exp_f32_e32 v10, v10
	v_exp_f32_e32 v11, v11
	v_exp_f32_e32 v4, v4
	v_exp_f32_e32 v5, v5
	v_exp_f32_e32 v136, v136
	v_exp_f32_e32 v137, v137
	v_pk_add_f32 v[8:9], v[8:9], 1.0 op_sel_hi:[1,0]
	v_pk_add_f32 v[10:11], v[10:11], 1.0 op_sel_hi:[1,0]
	v_pk_add_f32 v[4:5], v[4:5], 1.0 op_sel_hi:[1,0]
	v_pk_add_f32 v[136:137], v[136:137], 1.0 op_sel_hi:[1,0]
	v_rcp_f32_e32 v8, v8
	v_rcp_f32_e32 v9, v9
	v_rcp_f32_e32 v10, v10
	v_rcp_f32_e32 v11, v11
	v_rcp_f32_e32 v4, v4
	v_rcp_f32_e32 v5, v5
	v_rcp_f32_e32 v136, v136
	v_rcp_f32_e32 v137, v137
	v_cvt_pk_bf16_f32 v132, v8, v9
	v_cvt_pk_bf16_f32 v133, v10, v11
	v_cvt_pk_bf16_f32 v134, v4, v5
	s_mov_b64 s[100:101], 0x300
	v_lshl_add_u64 v[2:3], v[2:3], 0, s[100:101]
